# P1 counted epilogue waits plus removal of 64 dead hazard nops in the P12 boundary-row store section (cvt sources are long-finished accumulators)
# speedup vs baseline: 1.0033x; 1.0033x over previous
.Lmy_prio_skip5:
.LBB0_914:
	ds_read_b128 v[128:131], v187
	ds_read_b128 v[132:135], v187 offset:1024
	ds_read_b128 v[136:139], v187 offset:2048
	ds_read_b128 v[140:143], v187 offset:3072
	ds_read_b128 v[144:147], v188
	ds_read_b128 v[148:151], v188 offset:1024
	ds_read_b128 v[152:155], v188 offset:2048
	ds_read_b128 v[156:159], v188 offset:3072
	s_add_u32 s52, s50, 0x100
	s_addc_u32 s53, s51, 0
	s_cmp_eq_u32 s96, 60
	s_cselect_b32 s57, s41, s53
	s_cselect_b32 s56, s47, s52
	s_cselect_b32 s55, s39, s49
	s_cselect_b32 s54, s34, s35
	s_add_i32 m0, s67, 0xc000
	ds_read_b128 v[178:181], v189
	ds_read_b128 v[192:195], v189 offset:1024
	ds_read_b128 v[196:199], v189 offset:2048
	ds_read_b128 v[200:203], v189 offset:3072
	ds_read_b128 v[204:207], v189 offset:4096
	ds_read_b128 v[208:211], v189 offset:5120
	ds_read_b128 v[212:215], v189 offset:6144
	ds_read_b128 v[216:219], v189 offset:7168
	global_load_lds_dwordx4 v170, s[50:51]
	s_add_i32 m0, s67, 0xe000
	s_nop 0
	global_load_lds_dwordx4 v172, s[50:51]
	s_waitcnt vmcnt(8)
	s_waitcnt lgkmcnt(0)
	s_barrier
	s_waitcnt lgkmcnt(0)
	v_mfma_f32_16x16x32_bf16 v[124:127], v[128:131], v[178:181], v[124:127]
	v_mfma_f32_16x16x32_bf16 v[60:63], v[136:139], v[178:181], v[60:63]
	v_mfma_f32_16x16x32_bf16 v[116:119], v[128:131], v[196:199], v[116:119]
	v_mfma_f32_16x16x32_bf16 v[56:59], v[136:139], v[196:199], v[56:59]
	v_mfma_f32_16x16x32_bf16 v[108:111], v[128:131], v[204:207], v[108:111]
	v_mfma_f32_16x16x32_bf16 v[44:47], v[136:139], v[204:207], v[44:47]
	v_mfma_f32_16x16x32_bf16 v[104:107], v[128:131], v[212:215], v[104:107]
	v_mfma_f32_16x16x32_bf16 v[40:43], v[136:139], v[212:215], v[40:43]
	v_mfma_f32_16x16x32_bf16 v[124:127], v[132:135], v[192:195], v[124:127]
	v_mfma_f32_16x16x32_bf16 v[60:63], v[140:143], v[192:195], v[60:63]
	v_mfma_f32_16x16x32_bf16 v[116:119], v[132:135], v[200:203], v[116:119]
	v_mfma_f32_16x16x32_bf16 v[56:59], v[140:143], v[200:203], v[56:59]
	v_mfma_f32_16x16x32_bf16 v[108:111], v[132:135], v[208:211], v[108:111]
	v_mfma_f32_16x16x32_bf16 v[44:47], v[140:143], v[208:211], v[44:47]
	v_mfma_f32_16x16x32_bf16 v[104:107], v[132:135], v[216:219], v[104:107]
	v_mfma_f32_16x16x32_bf16 v[40:43], v[140:143], v[216:219], v[40:43]
	v_mfma_f32_16x16x32_bf16 v[120:123], v[144:147], v[178:181], v[120:123]
	v_mfma_f32_16x16x32_bf16 v[52:55], v[152:155], v[178:181], v[52:55]
	v_mfma_f32_16x16x32_bf16 v[112:115], v[144:147], v[196:199], v[112:115]
	v_mfma_f32_16x16x32_bf16 v[48:51], v[152:155], v[196:199], v[48:51]
	v_mfma_f32_16x16x32_bf16 v[100:103], v[144:147], v[204:207], v[100:103]
	v_mfma_f32_16x16x32_bf16 v[36:39], v[152:155], v[204:207], v[36:39]
	v_mfma_f32_16x16x32_bf16 v[96:99], v[144:147], v[212:215], v[96:99]
	v_mfma_f32_16x16x32_bf16 v[32:35], v[152:155], v[212:215], v[32:35]
	v_mfma_f32_16x16x32_bf16 v[120:123], v[148:151], v[192:195], v[120:123]
	v_mfma_f32_16x16x32_bf16 v[52:55], v[156:159], v[192:195], v[52:55]
	v_mfma_f32_16x16x32_bf16 v[112:115], v[148:151], v[200:203], v[112:115]
	v_mfma_f32_16x16x32_bf16 v[48:51], v[156:159], v[200:203], v[48:51]
	v_mfma_f32_16x16x32_bf16 v[100:103], v[148:151], v[208:211], v[100:103]
	v_mfma_f32_16x16x32_bf16 v[36:39], v[156:159], v[208:211], v[36:39]
	v_mfma_f32_16x16x32_bf16 v[96:99], v[148:151], v[216:219], v[96:99]
	v_mfma_f32_16x16x32_bf16 v[32:35], v[156:159], v[216:219], v[32:35]
	s_barrier
	s_add_i32 s50, s92, s66
	s_mov_b32 m0, s50
	ds_read_b128 v[178:181], v189 offset:16384
	ds_read_b128 v[192:195], v189 offset:17408
	ds_read_b128 v[196:199], v189 offset:18432
	ds_read_b128 v[200:203], v189 offset:19456
	ds_read_b128 v[204:207], v189 offset:20480
	ds_read_b128 v[208:211], v189 offset:21504
	ds_read_b128 v[212:215], v189 offset:22528
	ds_read_b128 v[216:219], v189 offset:23552
	global_load_lds_dwordx4 v164, s[54:55]
	s_add_i32 m0, s50, 0x2000
	s_add_u32 s50, s54, 0x100000
	v_lshl_add_u64 v[182:183], s[54:55], 0, v[168:169]
	s_addc_u32 s51, s55, 0
	s_add_i32 s97, s93, s66
	global_load_lds_dwordx4 v168, s[54:55]
	s_mov_b32 m0, s97
	global_load_lds_dwordx4 v164, s[50:51]
	s_add_i32 m0, s97, 0x2000
	s_nop 0
	global_load_lds_dwordx4 v168, s[50:51]
	s_mov_b32 m0, s67
	s_nop 0
	global_load_lds_dwordx4 v162, s[56:57]
	s_mov_b32 m0, s68
	s_nop 0
	global_load_lds_dwordx4 v166, s[56:57]
	s_waitcnt vmcnt(8)
	s_waitcnt lgkmcnt(0)
	s_barrier
	s_waitcnt lgkmcnt(0)
	v_mfma_f32_16x16x32_bf16 v[92:95], v[128:131], v[178:181], v[92:95]
	v_mfma_f32_16x16x32_bf16 v[28:31], v[136:139], v[178:181], v[28:31]
	v_mfma_f32_16x16x32_bf16 v[84:87], v[128:131], v[196:199], v[84:87]
	v_mfma_f32_16x16x32_bf16 v[24:27], v[136:139], v[196:199], v[24:27]
	v_mfma_f32_16x16x32_bf16 v[76:79], v[128:131], v[204:207], v[76:79]
	v_mfma_f32_16x16x32_bf16 v[12:15], v[136:139], v[204:207], v[12:15]
	v_mfma_f32_16x16x32_bf16 v[72:75], v[128:131], v[212:215], v[72:75]
	v_mfma_f32_16x16x32_bf16 v[8:11], v[136:139], v[212:215], v[8:11]
	v_mfma_f32_16x16x32_bf16 v[92:95], v[132:135], v[192:195], v[92:95]
	v_mfma_f32_16x16x32_bf16 v[28:31], v[140:143], v[192:195], v[28:31]
	v_mfma_f32_16x16x32_bf16 v[84:87], v[132:135], v[200:203], v[84:87]
	v_mfma_f32_16x16x32_bf16 v[24:27], v[140:143], v[200:203], v[24:27]
	v_mfma_f32_16x16x32_bf16 v[76:79], v[132:135], v[208:211], v[76:79]
	v_mfma_f32_16x16x32_bf16 v[12:15], v[140:143], v[208:211], v[12:15]
	v_mfma_f32_16x16x32_bf16 v[72:75], v[132:135], v[216:219], v[72:75]
	v_mfma_f32_16x16x32_bf16 v[8:11], v[140:143], v[216:219], v[8:11]
	v_mfma_f32_16x16x32_bf16 v[88:91], v[144:147], v[178:181], v[88:91]
	v_mfma_f32_16x16x32_bf16 v[20:23], v[152:155], v[178:181], v[20:23]
	v_mfma_f32_16x16x32_bf16 v[80:83], v[144:147], v[196:199], v[80:83]
	v_mfma_f32_16x16x32_bf16 v[16:19], v[152:155], v[196:199], v[16:19]
	v_mfma_f32_16x16x32_bf16 v[68:71], v[144:147], v[204:207], v[68:71]
	v_mfma_f32_16x16x32_bf16 v[4:7], v[152:155], v[204:207], v[4:7]
	v_mfma_f32_16x16x32_bf16 v[64:67], v[144:147], v[212:215], v[64:67]
	v_mfma_f32_16x16x32_bf16 v[0:3], v[152:155], v[212:215], v[0:3]
	v_mfma_f32_16x16x32_bf16 v[88:91], v[148:151], v[192:195], v[88:91]
	v_mfma_f32_16x16x32_bf16 v[20:23], v[156:159], v[192:195], v[20:23]
	v_mfma_f32_16x16x32_bf16 v[80:83], v[148:151], v[200:203], v[80:83]
	v_mfma_f32_16x16x32_bf16 v[16:19], v[156:159], v[200:203], v[16:19]
	v_mfma_f32_16x16x32_bf16 v[68:71], v[148:151], v[208:211], v[68:71]
	v_mfma_f32_16x16x32_bf16 v[4:7], v[156:159], v[208:211], v[4:7]
	v_mfma_f32_16x16x32_bf16 v[64:67], v[148:151], v[216:219], v[64:67]
	v_mfma_f32_16x16x32_bf16 v[0:3], v[156:159], v[216:219], v[0:3]
	s_barrier
	s_add_i32 s97, 0, 0x18000
	s_add_i32 vcc_lo, 0, 0x1c000
	v_add_u32_e32 v140, s97, v184
	v_add_u32_e32 v156, vcc_lo, v184
	ds_read_b128 v[128:131], v140
	ds_read_b128 v[132:135], v140 offset:1024
	ds_read_b128 v[136:139], v140 offset:2048
	ds_read_b128 v[140:143], v140 offset:3072
	ds_read_b128 v[144:147], v156
	ds_read_b128 v[148:151], v156 offset:1024
	ds_read_b128 v[152:155], v156 offset:2048
	ds_read_b128 v[156:159], v156 offset:3072
	s_add_u32 s50, s56, 0x100000
	s_addc_u32 s51, s57, 0
	s_mov_b32 m0, s69
	ds_read_b128 v[178:181], v189 offset:32768
	ds_read_b128 v[192:195], v189 offset:33792
	ds_read_b128 v[196:199], v189 offset:34816
	ds_read_b128 v[200:203], v189 offset:35840
	ds_read_b128 v[204:207], v189 offset:36864
	ds_read_b128 v[208:211], v189 offset:37888
	ds_read_b128 v[212:215], v189 offset:38912
	ds_read_b128 v[216:219], v189 offset:39936
	global_load_lds_dwordx4 v162, s[50:51]
	s_mov_b32 m0, s76
	s_nop 0
	global_load_lds_dwordx4 v166, s[50:51]
	s_waitcnt vmcnt(8)
	s_waitcnt lgkmcnt(0)
	s_barrier
	s_waitcnt lgkmcnt(0)
	v_mfma_f32_16x16x32_bf16 v[124:127], v[128:131], v[178:181], v[124:127]
	v_mfma_f32_16x16x32_bf16 v[60:63], v[136:139], v[178:181], v[60:63]
	v_mfma_f32_16x16x32_bf16 v[116:119], v[128:131], v[196:199], v[116:119]
	v_mfma_f32_16x16x32_bf16 v[56:59], v[136:139], v[196:199], v[56:59]
	v_mfma_f32_16x16x32_bf16 v[108:111], v[128:131], v[204:207], v[108:111]
	v_mfma_f32_16x16x32_bf16 v[44:47], v[136:139], v[204:207], v[44:47]
	v_mfma_f32_16x16x32_bf16 v[104:107], v[128:131], v[212:215], v[104:107]
	v_mfma_f32_16x16x32_bf16 v[40:43], v[136:139], v[212:215], v[40:43]
	v_mfma_f32_16x16x32_bf16 v[124:127], v[132:135], v[192:195], v[124:127]
	v_mfma_f32_16x16x32_bf16 v[60:63], v[140:143], v[192:195], v[60:63]
	v_mfma_f32_16x16x32_bf16 v[116:119], v[132:135], v[200:203], v[116:119]
	v_mfma_f32_16x16x32_bf16 v[56:59], v[140:143], v[200:203], v[56:59]
	v_mfma_f32_16x16x32_bf16 v[108:111], v[132:135], v[208:211], v[108:111]
	v_mfma_f32_16x16x32_bf16 v[44:47], v[140:143], v[208:211], v[44:47]
	v_mfma_f32_16x16x32_bf16 v[104:107], v[132:135], v[216:219], v[104:107]
	v_mfma_f32_16x16x32_bf16 v[40:43], v[140:143], v[216:219], v[40:43]
	v_mfma_f32_16x16x32_bf16 v[120:123], v[144:147], v[178:181], v[120:123]
	v_mfma_f32_16x16x32_bf16 v[52:55], v[152:155], v[178:181], v[52:55]
	v_mfma_f32_16x16x32_bf16 v[112:115], v[144:147], v[196:199], v[112:115]
	v_mfma_f32_16x16x32_bf16 v[48:51], v[152:155], v[196:199], v[48:51]
	v_mfma_f32_16x16x32_bf16 v[100:103], v[144:147], v[204:207], v[100:103]
	v_mfma_f32_16x16x32_bf16 v[36:39], v[152:155], v[204:207], v[36:39]
	v_mfma_f32_16x16x32_bf16 v[96:99], v[144:147], v[212:215], v[96:99]
	v_mfma_f32_16x16x32_bf16 v[32:35], v[152:155], v[212:215], v[32:35]
	v_mfma_f32_16x16x32_bf16 v[120:123], v[148:151], v[192:195], v[120:123]
	v_mfma_f32_16x16x32_bf16 v[52:55], v[156:159], v[192:195], v[52:55]
	v_mfma_f32_16x16x32_bf16 v[112:115], v[148:151], v[200:203], v[112:115]
	v_mfma_f32_16x16x32_bf16 v[48:51], v[156:159], v[200:203], v[48:51]
	v_mfma_f32_16x16x32_bf16 v[100:103], v[148:151], v[208:211], v[100:103]
	v_mfma_f32_16x16x32_bf16 v[36:39], v[156:159], v[208:211], v[36:39]
	v_mfma_f32_16x16x32_bf16 v[96:99], v[148:151], v[216:219], v[96:99]
	v_mfma_f32_16x16x32_bf16 v[32:35], v[156:159], v[216:219], v[32:35]
	s_barrier
	s_add_i32 s50, s97, s66
	s_mov_b32 m0, s50
	ds_read_b128 v[178:181], v189 offset:49152
	ds_read_b128 v[192:195], v189 offset:50176
	ds_read_b128 v[196:199], v189 offset:51200
	ds_read_b128 v[200:203], v189 offset:52224
	ds_read_b128 v[204:207], v189 offset:53248
	ds_read_b128 v[208:211], v189 offset:54272
	ds_read_b128 v[212:215], v189 offset:55296
	ds_read_b128 v[216:219], v189 offset:56320
	s_add_u32 s100, s54, 0x80
	s_addc_u32 s101, s55, 0
	global_load_lds_dwordx4 v164, s[100:101]
	s_add_i32 m0, s50, 0x2000
	s_add_u32 s50, s54, 0x100080
	v_lshl_add_u64 v[160:161], v[182:183], 0, s[10:11]
	s_addc_u32 s51, s55, 0
	s_add_i32 s54, vcc_lo, s66
	global_load_lds_dwordx4 v[160:161], off
	s_mov_b32 m0, s54
	s_nop 0
	global_load_lds_dwordx4 v164, s[50:51]
	s_add_i32 m0, s54, 0x2000
	s_nop 0
	global_load_lds_dwordx4 v168, s[50:51]
	s_mov_b32 m0, s84
	s_nop 0
	s_add_u32 s100, s56, 0x80
	s_addc_u32 s101, s57, 0
	global_load_lds_dwordx4 v162, s[100:101]
	s_mov_b32 m0, s85
	s_nop 0
	s_add_u32 s100, s56, 0x80
	s_addc_u32 s101, s57, 0
	global_load_lds_dwordx4 v166, s[100:101]
	s_add_i32 s96, s96, 2
	s_add_u32 s35, s35, 0x100
	s_addc_u32 s49, s49, 0
	s_cmp_gt_u32 s96, 61
	s_waitcnt vmcnt(8)
	s_waitcnt lgkmcnt(0)
	s_barrier
	s_waitcnt lgkmcnt(0)
	v_mfma_f32_16x16x32_bf16 v[92:95], v[128:131], v[178:181], v[92:95]
	v_mfma_f32_16x16x32_bf16 v[28:31], v[136:139], v[178:181], v[28:31]
	v_mfma_f32_16x16x32_bf16 v[84:87], v[128:131], v[196:199], v[84:87]
	v_mfma_f32_16x16x32_bf16 v[24:27], v[136:139], v[196:199], v[24:27]
	v_mfma_f32_16x16x32_bf16 v[76:79], v[128:131], v[204:207], v[76:79]
	v_mfma_f32_16x16x32_bf16 v[12:15], v[136:139], v[204:207], v[12:15]
	v_mfma_f32_16x16x32_bf16 v[72:75], v[128:131], v[212:215], v[72:75]
	v_mfma_f32_16x16x32_bf16 v[8:11], v[136:139], v[212:215], v[8:11]
	v_mfma_f32_16x16x32_bf16 v[92:95], v[132:135], v[192:195], v[92:95]
	v_mfma_f32_16x16x32_bf16 v[28:31], v[140:143], v[192:195], v[28:31]
	v_mfma_f32_16x16x32_bf16 v[84:87], v[132:135], v[200:203], v[84:87]
	v_mfma_f32_16x16x32_bf16 v[24:27], v[140:143], v[200:203], v[24:27]
	v_mfma_f32_16x16x32_bf16 v[76:79], v[132:135], v[208:211], v[76:79]
	v_mfma_f32_16x16x32_bf16 v[12:15], v[140:143], v[208:211], v[12:15]
	v_mfma_f32_16x16x32_bf16 v[72:75], v[132:135], v[216:219], v[72:75]
	v_mfma_f32_16x16x32_bf16 v[8:11], v[140:143], v[216:219], v[8:11]
	v_mfma_f32_16x16x32_bf16 v[88:91], v[144:147], v[178:181], v[88:91]
	v_mfma_f32_16x16x32_bf16 v[20:23], v[152:155], v[178:181], v[20:23]
	v_mfma_f32_16x16x32_bf16 v[80:83], v[144:147], v[196:199], v[80:83]
	v_mfma_f32_16x16x32_bf16 v[16:19], v[152:155], v[196:199], v[16:19]
	v_mfma_f32_16x16x32_bf16 v[68:71], v[144:147], v[204:207], v[68:71]
	v_mfma_f32_16x16x32_bf16 v[4:7], v[152:155], v[204:207], v[4:7]
	v_mfma_f32_16x16x32_bf16 v[64:67], v[144:147], v[212:215], v[64:67]
	v_mfma_f32_16x16x32_bf16 v[0:3], v[152:155], v[212:215], v[0:3]
	v_mfma_f32_16x16x32_bf16 v[88:91], v[148:151], v[192:195], v[88:91]
	v_mfma_f32_16x16x32_bf16 v[20:23], v[156:159], v[192:195], v[20:23]
	v_mfma_f32_16x16x32_bf16 v[80:83], v[148:151], v[200:203], v[80:83]
	v_mfma_f32_16x16x32_bf16 v[16:19], v[156:159], v[200:203], v[16:19]
	v_mfma_f32_16x16x32_bf16 v[68:71], v[148:151], v[208:211], v[68:71]
	v_mfma_f32_16x16x32_bf16 v[4:7], v[156:159], v[208:211], v[4:7]
	v_mfma_f32_16x16x32_bf16 v[64:67], v[148:151], v[216:219], v[64:67]
	v_mfma_f32_16x16x32_bf16 v[0:3], v[156:159], v[216:219], v[0:3]
	s_barrier
	s_mov_b64 s[50:51], s[52:53]
	s_cbranch_scc0 .LBB0_914
	s_setprio 0
	s_lshl_b32 s34, s46, 2
	v_lshl_or_b32 v178, s48, 7, v186
	s_add_i32 s34, s34, s65
	v_ashrrev_i32_e32 v179, 31, v178
	s_mul_hi_i32 s35, s34, 0x30000
	s_mul_i32 s39, s34, 0x30000
	v_lshlrev_b64 v[144:145], 2, v[178:179]
	v_readlane_b32 s24, v254, 31
	v_readlane_b32 s25, v254, 32
	v_readlane_b32 s26, v254, 33
	v_readlane_b32 s27, v254, 34
	v_lshl_add_u64 v[180:181], s[24:25], 0, v[144:145]
	v_lshl_add_u64 v[136:137], s[88:89], 0, v[144:145]
	global_load_dwordx4 v[128:131], v[180:181], off
	global_load_dwordx4 v[150:153], v[136:137], off
	v_lshl_add_u64 v[182:183], s[26:27], 0, v[144:145]
	v_lshl_add_u64 v[136:137], s[36:37], 0, v[144:145]
	global_load_dwordx4 v[132:135], v[182:183], off
	v_lshl_add_u64 v[140:141], s[58:59], 0, v[144:145]
	global_load_dwordx4 v[136:139], v[136:137], off
	v_lshl_add_u64 v[146:147], s[94:95], 0, v[144:145]
	global_load_dwordx4 v[140:143], v[140:141], off
	s_nop 0
	global_load_dwordx4 v[154:157], v[146:147], off
	v_lshl_add_u64 v[146:147], s[60:61], 0, v[144:145]
	v_lshl_add_u64 v[148:149], s[62:63], 0, v[144:145]
	global_load_dwordx4 v[144:147], v[146:147], off
	s_nop 0
	global_load_dwordx4 v[158:161], v[148:149], off
	s_and_saveexec_b64 s[48:49], s[0:1]
	s_cbranch_execz .LBB0_917
	s_add_u32 s50, s79, s39
	s_addc_u32 s51, s81, s35
	v_lshl_add_u64 v[248:249], v[178:179], 1, s[50:51]
	v_add_co_u32_e32 v250, vcc, s78, v248
	v_cvt_pk_bf16_f32 v244, v124, v125
	v_cvt_pk_bf16_f32 v245, v126, v127
	v_cvt_pk_bf16_f32 v246, v60, v61
	v_cvt_pk_bf16_f32 v247, v62, v63
	s_nop 1
	v_addc_co_u32_e32 v251, vcc, 0, v249, vcc
	s_mov_b32 s17, 0xc000
	global_store_dwordx4 v[248:249], v[244:247], off
	s_nop 1
	v_cvt_pk_bf16_f32 v244, v120, v121
	v_cvt_pk_bf16_f32 v245, v122, v123
	v_cvt_pk_bf16_f32 v246, v52, v53
	v_cvt_pk_bf16_f32 v247, v54, v55
	global_store_dwordx4 v[250:251], v[244:247], off
	v_add_co_u32_e32 v250, vcc, s17, v248
	s_nop 0
	v_cvt_pk_bf16_f32 v244, v116, v117
	v_cvt_pk_bf16_f32 v245, v118, v119
	v_cvt_pk_bf16_f32 v246, v56, v57
	v_cvt_pk_bf16_f32 v247, v58, v59
	s_nop 0
	v_addc_co_u32_e32 v251, vcc, 0, v249, vcc
	v_add_co_u32_e32 v248, vcc, 0x12000, v248
	global_store_dwordx4 v[250:251], v[244:247], off
	s_nop 0
	v_addc_co_u32_e32 v249, vcc, 0, v249, vcc
	v_cvt_pk_bf16_f32 v244, v112, v113
	v_cvt_pk_bf16_f32 v245, v114, v115
	v_cvt_pk_bf16_f32 v246, v48, v49
	v_cvt_pk_bf16_f32 v247, v50, v51
	global_store_dwordx4 v[248:249], v[244:247], off
.LBB0_917:
	s_or_b64 exec, exec, s[48:49]
	s_and_saveexec_b64 s[48:49], s[4:5]
	s_mov_b32 s96, s14
	s_cbranch_execz .LBB0_919
	s_add_u32 s50, s79, s39
	s_addc_u32 s51, s81, s35
	v_lshl_add_u64 v[248:249], v[178:179], 1, s[50:51]
	s_mov_b32 s14, 0x18000
	v_add_co_u32_e32 v250, vcc, s14, v248
	s_mov_b32 s14, 0x1e000
	s_nop 0
	v_addc_co_u32_e32 v251, vcc, 0, v249, vcc
	v_cvt_pk_bf16_f32 v244, v108, v109
	v_cvt_pk_bf16_f32 v245, v110, v111
	v_cvt_pk_bf16_f32 v246, v44, v45
	v_cvt_pk_bf16_f32 v247, v46, v47
	global_store_dwordx4 v[250:251], v[244:247], off
	v_add_co_u32_e32 v250, vcc, s14, v248
	s_mov_b32 s14, 0x24000
	s_nop 0
	v_addc_co_u32_e32 v251, vcc, 0, v249, vcc
	v_cvt_pk_bf16_f32 v244, v100, v101
	v_cvt_pk_bf16_f32 v245, v102, v103
	v_cvt_pk_bf16_f32 v246, v36, v37
	v_cvt_pk_bf16_f32 v247, v38, v39
	global_store_dwordx4 v[250:251], v[244:247], off
	v_add_co_u32_e32 v250, vcc, s14, v248
	s_nop 0
	v_cvt_pk_bf16_f32 v244, v104, v105
	v_cvt_pk_bf16_f32 v245, v106, v107
	v_cvt_pk_bf16_f32 v246, v40, v41
	v_cvt_pk_bf16_f32 v247, v42, v43
	s_nop 0
	v_addc_co_u32_e32 v251, vcc, 0, v249, vcc
	v_add_co_u32_e32 v248, vcc, 0x2a000, v248
	global_store_dwordx4 v[250:251], v[244:247], off
	s_nop 0
	v_addc_co_u32_e32 v249, vcc, 0, v249, vcc
	v_cvt_pk_bf16_f32 v244, v96, v97
	v_cvt_pk_bf16_f32 v245, v98, v99
	v_cvt_pk_bf16_f32 v246, v32, v33
	v_cvt_pk_bf16_f32 v247, v34, v35
	global_store_dwordx4 v[248:249], v[244:247], off
.LBB0_919:
	s_or_b64 exec, exec, s[48:49]
	s_add_i32 s35, s34, 2
	s_mul_hi_i32 s34, s35, 0x30000
	s_mul_i32 s35, s35, 0x30000
	s_and_saveexec_b64 s[48:49], s[0:1]
	s_cbranch_execz .LBB0_921
	s_add_u32 s50, s79, s35
	s_addc_u32 s51, s81, s34
	v_lshl_add_u64 v[248:249], v[178:179], 1, s[50:51]
	v_add_co_u32_e32 v250, vcc, s78, v248
	v_cvt_pk_bf16_f32 v244, v92, v93
	v_cvt_pk_bf16_f32 v245, v94, v95
	v_cvt_pk_bf16_f32 v246, v28, v29
	v_cvt_pk_bf16_f32 v247, v30, v31
	s_nop 1
	v_addc_co_u32_e32 v251, vcc, 0, v249, vcc
	s_mov_b32 s14, 0xc000
	global_store_dwordx4 v[248:249], v[244:247], off
	s_nop 1
	v_cvt_pk_bf16_f32 v244, v88, v89
	v_cvt_pk_bf16_f32 v245, v90, v91
	v_cvt_pk_bf16_f32 v246, v20, v21
	v_cvt_pk_bf16_f32 v247, v22, v23
	global_store_dwordx4 v[250:251], v[244:247], off
	v_add_co_u32_e32 v250, vcc, s14, v248
	s_nop 0
	v_cvt_pk_bf16_f32 v244, v84, v85
	v_cvt_pk_bf16_f32 v245, v86, v87
	v_cvt_pk_bf16_f32 v246, v24, v25
	v_cvt_pk_bf16_f32 v247, v26, v27
	s_nop 0
	v_addc_co_u32_e32 v251, vcc, 0, v249, vcc
	v_add_co_u32_e32 v248, vcc, 0x12000, v248
	global_store_dwordx4 v[250:251], v[244:247], off
	s_nop 0
	v_addc_co_u32_e32 v249, vcc, 0, v249, vcc
	v_cvt_pk_bf16_f32 v244, v80, v81
	v_cvt_pk_bf16_f32 v245, v82, v83
	v_cvt_pk_bf16_f32 v246, v16, v17
	v_cvt_pk_bf16_f32 v247, v18, v19
	global_store_dwordx4 v[248:249], v[244:247], off
.LBB0_921:
	s_or_b64 exec, exec, s[48:49]
	s_and_saveexec_b64 s[48:49], s[4:5]
	v_readlane_b32 s97, v254, 56
	s_mov_b32 s54, s16
	s_cbranch_execz .LBB0_923
	s_add_u32 s50, s79, s35
	s_addc_u32 s51, s81, s34
	v_lshl_add_u64 v[248:249], v[178:179], 1, s[50:51]
	s_mov_b32 s14, 0x18000
	v_add_co_u32_e32 v250, vcc, s14, v248
	s_mov_b32 s14, 0x1e000
	s_nop 0
	v_addc_co_u32_e32 v251, vcc, 0, v249, vcc
	v_cvt_pk_bf16_f32 v244, v76, v77
	v_cvt_pk_bf16_f32 v245, v78, v79
	v_cvt_pk_bf16_f32 v246, v12, v13
	v_cvt_pk_bf16_f32 v247, v14, v15
	global_store_dwordx4 v[250:251], v[244:247], off
	v_add_co_u32_e32 v250, vcc, s14, v248
	s_mov_b32 s14, 0x24000
	s_nop 0
	v_addc_co_u32_e32 v251, vcc, 0, v249, vcc
	v_cvt_pk_bf16_f32 v244, v68, v69
	v_cvt_pk_bf16_f32 v245, v70, v71
	v_cvt_pk_bf16_f32 v246, v4, v5
	v_cvt_pk_bf16_f32 v247, v6, v7
	global_store_dwordx4 v[250:251], v[244:247], off
	v_add_co_u32_e32 v250, vcc, s14, v248
	s_nop 0
	v_cvt_pk_bf16_f32 v244, v72, v73
	v_cvt_pk_bf16_f32 v245, v74, v75
	v_cvt_pk_bf16_f32 v246, v8, v9
	v_cvt_pk_bf16_f32 v247, v10, v11
	s_nop 0
	v_addc_co_u32_e32 v251, vcc, 0, v249, vcc
	v_add_co_u32_e32 v248, vcc, 0x2a000, v248
	global_store_dwordx4 v[250:251], v[244:247], off
	s_nop 0
	v_addc_co_u32_e32 v249, vcc, 0, v249, vcc
	v_cvt_pk_bf16_f32 v244, v64, v65
	v_cvt_pk_bf16_f32 v245, v66, v67
	v_cvt_pk_bf16_f32 v246, v0, v1
	v_cvt_pk_bf16_f32 v247, v2, v3
	global_store_dwordx4 v[248:249], v[244:247], off
